# v12 + unit prologues: dropped the vmcnt(0) drain before the unit-start barrier in MLA part1 and tile64 part2 so Q loads overlap the first K/V LDS-DMA
# speedup vs baseline: 1.0064x; 1.0064x over previous
.LBB0_783:
	s_ashr_i32 s2, s4, 7
	s_sub_i32 s5, 1, s2
	s_and_b32 s2, s4, 0x78
	v_readlane_b32 s3, v250, 0
	s_add_i32 s2, s2, s3
	s_and_b32 s6, s4, 7
	v_lshl_or_b32 v158, s2, 5, v182
	s_mul_i32 s40, s6, 0x1100
	v_ashrrev_i32_e32 v159, 31, v158
	v_lshl_add_u64 v[0:1], s[40:41], 0, v[158:159]
	v_mad_u64_u32 v[2:3], s[2:3], v0, s21, v[186:187]
	s_mul_i32 s8, s6, 0x198000
	v_readlane_b32 s2, v251, 37
	v_readlane_b32 s3, v251, 38
	s_add_u32 s2, s2, s8
	s_addc_u32 s3, s3, 0
	s_mul_i32 s40, s5, 34
	s_mul_i32 s5, s5, 0xcc000
	s_mul_hi_u32 s9, s40, 0x6000
	s_add_u32 s2, s2, s5
	v_mad_i32_i24 v3, v1, s21, v3
	s_addc_u32 s3, s3, s9
	global_load_dwordx4 v[82:85], v[2:3], off
	global_load_dwordx4 v[86:89], v[2:3], off offset:32
	global_load_dwordx4 v[90:93], v[2:3], off offset:64
	global_load_dwordx4 v[112:115], v[2:3], off offset:96
	global_load_dwordx4 v[116:119], v[2:3], off offset:128
	global_load_dwordx4 v[120:123], v[2:3], off offset:160
	global_load_dwordx4 v[124:127], v[2:3], off offset:192
	global_load_dwordx4 v[128:131], v[2:3], off offset:224
	global_load_dwordx4 v[132:135], v[2:3], off offset:256
	global_load_dwordx4 v[136:139], v[2:3], off offset:288
	global_load_dwordx4 v[140:143], v[2:3], off offset:320
	global_load_dwordx4 v[144:147], v[2:3], off offset:352
	v_lshl_add_u64 v[0:1], s[2:3], 0, v[152:153]
	s_mul_i32 s10, s6, 0x110000
	v_readlane_b32 s2, v252, 15
	v_readlane_b32 s3, v252, 16
	s_add_u32 s6, s2, s10
	s_addc_u32 s7, s3, 0
	s_lshl_b64 s[2:3], s[40:41], 14
	s_add_u32 s6, s6, s2
	s_addc_u32 s7, s7, s3
	v_lshl_add_u64 v[2:3], s[6:7], 0, v[152:153]
	s_add_i32 s6, s94, 0
	v_lshl_add_u64 v[0:1], v[0:1], 0, s[94:95]
	s_mov_b32 m0, s6
	s_nop 0
	s_barrier
	global_load_lds_dwordx4 v[0:1], off
	v_lshl_add_u64 v[4:5], v[0:1], 0, s[72:73]
	s_add_i32 m0, s64, 0
	v_lshl_add_u64 v[0:1], v[0:1], 0, s[26:27]
	global_load_lds_dwordx4 v[4:5], off
	s_add_i32 m0, s65, 0
	v_lshl_add_u64 v[2:3], v[2:3], 0, s[94:95]
	global_load_lds_dwordx4 v[0:1], off
	s_add_i32 m0, s6, 0x3000
	v_lshl_add_u64 v[0:1], v[2:3], 0, s[72:73]
	global_load_lds_dwordx4 v[2:3], off
	s_add_i32 m0, s6, 0x8000
	s_add_u32 s2, s10, s2
	global_load_lds_dwordx4 v[0:1], off
	s_addc_u32 s3, 0, s3
	v_lshl_add_u64 v[160:161], v[156:157], 0, s[2:3]
	s_add_u32 s2, s8, s5
	v_mov_b32_e32 v96, v97
	s_addc_u32 s3, 0, s9
	v_mov_b32_e32 v98, v97
	v_mov_b32_e32 v99, v97
	v_mov_b32_e32 v100, v97
	v_mov_b32_e32 v101, v97
	v_mov_b32_e32 v102, v97
	v_mov_b32_e32 v103, v97
	v_mov_b32_e32 v104, v97
	v_mov_b32_e32 v105, v97
	v_mov_b32_e32 v106, v97
	v_mov_b32_e32 v107, v97
	v_mov_b32_e32 v108, v97
	v_mov_b32_e32 v109, v97
	v_mov_b32_e32 v110, v97
	v_mov_b32_e32 v111, v97
	v_mov_b64_e32 v[48:49], v[96:97]
	v_mov_b64_e32 v[32:33], v[96:97]
	v_mov_b64_e32 v[16:17], v[96:97]
	v_mov_b64_e32 v[0:1], v[96:97]
	v_lshl_add_u64 v[162:163], v[156:157], 0, s[2:3]
	s_mov_b32 s2, 0
	v_mov_b32_e32 v80, 0xf149f2ca
	v_mov_b32_e32 v81, 0
	v_mov_b64_e32 v[50:51], v[98:99]
	v_mov_b64_e32 v[52:53], v[100:101]
	v_mov_b64_e32 v[54:55], v[102:103]
	v_mov_b64_e32 v[56:57], v[104:105]
	v_mov_b64_e32 v[58:59], v[106:107]
	v_mov_b64_e32 v[60:61], v[108:109]
	v_mov_b64_e32 v[62:63], v[110:111]
	v_mov_b64_e32 v[34:35], v[98:99]
	v_mov_b64_e32 v[36:37], v[100:101]
	v_mov_b64_e32 v[38:39], v[102:103]
	v_mov_b64_e32 v[40:41], v[104:105]
	v_mov_b64_e32 v[42:43], v[106:107]
	v_mov_b64_e32 v[44:45], v[108:109]
	v_mov_b64_e32 v[46:47], v[110:111]
	v_mov_b64_e32 v[18:19], v[98:99]
	v_mov_b64_e32 v[20:21], v[100:101]
	v_mov_b64_e32 v[22:23], v[102:103]
	v_mov_b64_e32 v[24:25], v[104:105]
	v_mov_b64_e32 v[26:27], v[106:107]
	v_mov_b64_e32 v[28:29], v[108:109]
	v_mov_b64_e32 v[30:31], v[110:111]
	v_mov_b64_e32 v[2:3], v[98:99]
	v_mov_b64_e32 v[4:5], v[100:101]
	v_mov_b64_e32 v[6:7], v[102:103]
	v_mov_b64_e32 v[8:9], v[104:105]
	v_mov_b64_e32 v[10:11], v[106:107]
	v_mov_b64_e32 v[12:13], v[108:109]
	v_mov_b64_e32 v[14:15], v[110:111]

.LBB0_817:
	v_lshl_add_u64 v[0:1], v[184:185], 1, v[0:1]
	global_load_dwordx4 v[114:117], v[0:1], off
	global_load_dwordx4 v[118:121], v[0:1], off offset:32
	global_load_dwordx4 v[122:125], v[0:1], off offset:64
	global_load_dwordx4 v[126:129], v[0:1], off offset:96
	s_xor_b64 s[8:9], s[0:1], -1
	s_and_b64 vcc, exec, s[8:9]
	s_nop 0
	s_barrier
	s_cbranch_vccnz .LBB0_821
	v_mov_b32_e32 v0, 0xff800000
	s_and_saveexec_b64 s[0:1], s[42:43]
	s_cbranch_execz .LBB0_820
	v_lshl_add_u64 v[0:1], v[148:149], 2, v[6:7]
	global_load_dword v0, v[0:1], off
	s_waitcnt vmcnt(0)
	v_mul_f32_e32 v0, 0x3fb8aa3b, v0
